# v40 + grid barrier release flattened: XCD members poll the top generation word directly, leader's per-XCD bump dropped
# baseline (speedup 1.0000x reference)
.LBB0_327:
	s_or_b64 exec, exec, s[4:5]
	v_cvt_f32_u32_e32 v5, v3
	s_waitcnt vmcnt(0)
	v_readfirstlane_b32 s3, v4
	v_sub_u32_e32 v4, 0, v3
	v_rcp_iflag_f32_e32 v5, v5
	v_add_u32_e32 v6, s3, v2
	v_mul_f32_e32 v5, 0x4f7ffffe, v5
	v_cvt_u32_f32_e32 v5, v5
	v_mul_lo_u32 v2, v4, v5
	v_mul_hi_u32 v2, v5, v2
	v_add_u32_e32 v2, v5, v2
	v_mul_hi_u32 v2, v6, v2
	v_mul_lo_u32 v4, v2, v3
	v_sub_u32_e32 v4, v6, v4
	v_add_u32_e32 v5, 1, v2
	v_cmp_ge_u32_e32 vcc, v4, v3
	s_nop 1
	v_cndmask_b32_e32 v2, v2, v5, vcc
	v_sub_u32_e32 v5, v4, v3
	v_cndmask_b32_e32 v4, v4, v5, vcc
	v_add_u32_e32 v5, 1, v2
	v_cmp_ge_u32_e32 vcc, v4, v3
	v_add_u32_e32 v4, 1, v6
	s_nop 0
	v_cndmask_b32_e32 v2, v2, v5, vcc
	v_mul_lo_u32 v5, v3, v2
	v_add_u32_e32 v3, v5, v3
	v_cmp_ne_u32_e32 vcc, v4, v3
	s_and_saveexec_b64 s[4:5], vcc
	s_xor_b64 s[4:5], exec, s[4:5]
	s_cbranch_execz .LBB0_341
	v_readlane_b32 s6, v253, 10
	s_waitcnt lgkmcnt(0)
	v_mov_b32_e32 v1, 0
	v_readlane_b32 s7, v253, 11
	s_nop 4
	global_load_dword v3, v1, s[6:7] sc1
	s_waitcnt vmcnt(0)
	v_cmp_eq_u32_e32 vcc, v3, v2
	s_and_saveexec_b64 s[6:7], vcc
	s_cbranch_execz .LBB0_340
	s_mov_b32 s3, 1
	s_mov_b64 s[8:9], 0
	s_branch .LBB0_331

.LBB0_335:
	v_readlane_b32 s12, v253, 10
	v_readlane_b32 s13, v253, 11
	s_add_i32 s3, s3, 1
	s_mov_b64 s[14:15], -1
	s_nop 2
	global_load_dword v3, v1, s[12:13] sc1
	s_waitcnt vmcnt(0)
	v_cmp_ne_u32_e32 vcc, v3, v2
	s_orn2_b64 s[12:13], vcc, exec
	s_branch .LBB0_330

.LBB0_358:
	s_or_b64 exec, exec, s[4:5]
	s_mov_b64 s[4:5], exec
	v_mbcnt_lo_u32_b32 v1, s4, 0
	v_mbcnt_hi_u32_b32 v1, s5, v1
	v_cmp_eq_u32_e32 vcc, 0, v1
	s_waitcnt vmcnt(0)
	buffer_inv sc1
	s_and_saveexec_b64 s[6:7], vcc
	s_cbranch_execz .LBB0_360
	s_bcnt1_i32_b64 s3, s[4:5]
	v_readlane_b32 s4, v253, 6
	v_mov_b32_e32 v1, 0
	v_mov_b32_e32 v2, s3
	v_readlane_b32 s5, v253, 7
	s_nop 4
.LBB0_360:
	s_or_b64 exec, exec, s[6:7]
	s_waitcnt vmcnt(0)

.LBB0_441:
	s_or_b64 exec, exec, s[4:5]
	s_mov_b64 s[4:5], exec
	v_mbcnt_lo_u32_b32 v1, s4, 0
	v_mbcnt_hi_u32_b32 v1, s5, v1
	v_cmp_eq_u32_e32 vcc, 0, v1
	s_waitcnt vmcnt(0)
	buffer_inv sc1
	s_and_saveexec_b64 s[6:7], vcc
	s_cbranch_execz .LBB0_443
	s_bcnt1_i32_b64 s3, s[4:5]
	v_readlane_b32 s4, v253, 6
	v_mov_b32_e32 v1, 0
	v_mov_b32_e32 v2, s3
	v_readlane_b32 s5, v253, 7
	s_nop 4
.LBB0_443:
	s_or_b64 exec, exec, s[6:7]
	s_waitcnt vmcnt(0)

.LBB0_591:
	s_or_b64 exec, exec, s[8:9]
	v_cvt_f32_u32_e32 v7, v5
	s_waitcnt vmcnt(0)
	v_readfirstlane_b32 s8, v6
	v_sub_u32_e32 v6, 0, v5
	v_rcp_iflag_f32_e32 v7, v7
	v_add_u32_e32 v8, s8, v2
	v_mul_f32_e32 v7, 0x4f7ffffe, v7
	v_cvt_u32_f32_e32 v7, v7
	v_mul_lo_u32 v2, v6, v7
	v_mul_hi_u32 v2, v7, v2
	v_add_u32_e32 v2, v7, v2
	v_mul_hi_u32 v2, v8, v2
	v_mul_lo_u32 v6, v2, v5
	v_sub_u32_e32 v6, v8, v6
	v_add_u32_e32 v7, 1, v2
	v_cmp_ge_u32_e32 vcc, v6, v5
	s_nop 1
	v_cndmask_b32_e32 v2, v2, v7, vcc
	v_sub_u32_e32 v7, v6, v5
	v_cndmask_b32_e32 v6, v6, v7, vcc
	v_add_u32_e32 v7, 1, v2
	v_cmp_ge_u32_e32 vcc, v6, v5
	v_add_u32_e32 v6, 1, v8
	s_nop 0
	v_cndmask_b32_e32 v2, v2, v7, vcc
	v_mul_lo_u32 v7, v5, v2
	v_add_u32_e32 v5, v7, v5
	v_cmp_ne_u32_e32 vcc, v6, v5
	s_and_saveexec_b64 s[8:9], vcc
	s_xor_b64 s[8:9], exec, s[8:9]
	s_cbranch_execz .LBB0_605
	v_readlane_b32 s10, v253, 10
	v_readlane_b32 s11, v253, 11
	s_waitcnt lgkmcnt(0)
	s_nop 3
	global_load_dword v4, v3, s[10:11] sc1
	s_waitcnt vmcnt(0)
	v_cmp_eq_u32_e32 vcc, v4, v2
	s_and_saveexec_b64 s[10:11], vcc
	s_cbranch_execz .LBB0_604
	s_mov_b32 s20, 1
	s_mov_b64 s[12:13], 0
	s_branch .LBB0_595

.LBB0_622:
	s_or_b64 exec, exec, s[8:9]
	s_mov_b64 s[8:9], exec
	v_mbcnt_lo_u32_b32 v2, s8, 0
	v_mbcnt_hi_u32_b32 v2, s9, v2
	v_cmp_eq_u32_e32 vcc, 0, v2
	s_waitcnt vmcnt(0)
	buffer_inv sc1
	s_and_saveexec_b64 s[10:11], vcc
	s_cbranch_execz .LBB0_624
	s_bcnt1_i32_b64 s8, s[8:9]
	v_mov_b32_e32 v2, s8
	v_readlane_b32 s8, v253, 6
	v_readlane_b32 s9, v253, 7
	s_nop 4
.LBB0_624:
	s_or_b64 exec, exec, s[10:11]
	s_waitcnt vmcnt(0)

.LBB0_724:
	s_or_b64 exec, exec, s[8:9]
	s_mov_b64 s[8:9], exec
	v_mbcnt_lo_u32_b32 v2, s8, 0
	v_mbcnt_hi_u32_b32 v2, s9, v2
	v_cmp_eq_u32_e32 vcc, 0, v2
	s_waitcnt vmcnt(0)
	buffer_inv sc1
	s_and_saveexec_b64 s[10:11], vcc
	s_cbranch_execz .LBB0_726
	s_bcnt1_i32_b64 s8, s[8:9]
	v_mov_b32_e32 v2, s8
	v_readlane_b32 s8, v253, 6
	v_readlane_b32 s9, v253, 7
	s_nop 4
.LBB0_726:
	s_or_b64 exec, exec, s[10:11]
	s_waitcnt vmcnt(0)

.LBB0_1099:
	s_or_b64 exec, exec, s[8:9]
	s_mov_b64 s[8:9], exec
	v_mbcnt_lo_u32_b32 v2, s8, 0
	v_mbcnt_hi_u32_b32 v2, s9, v2
	v_cmp_eq_u32_e32 vcc, 0, v2
	s_waitcnt vmcnt(0)
	buffer_inv sc1
	s_and_saveexec_b64 s[10:11], vcc
	s_cbranch_execz .LBB0_1101
	s_bcnt1_i32_b64 s8, s[8:9]
	v_mov_b32_e32 v2, s8
	v_readlane_b32 s8, v253, 6
	v_readlane_b32 s9, v253, 7
	s_nop 4
.LBB0_1101:
	s_or_b64 exec, exec, s[10:11]
	s_waitcnt vmcnt(0)

.LBB0_1156:
	s_or_b64 exec, exec, s[8:9]
	s_mov_b64 s[8:9], exec
	v_mbcnt_lo_u32_b32 v2, s8, 0
	v_mbcnt_hi_u32_b32 v2, s9, v2
	v_cmp_eq_u32_e32 vcc, 0, v2
	s_waitcnt vmcnt(0)
	buffer_inv sc1
	s_and_saveexec_b64 s[10:11], vcc
	s_cbranch_execz .LBB0_1158
	s_bcnt1_i32_b64 s8, s[8:9]
	v_mov_b32_e32 v2, s8
	v_readlane_b32 s8, v253, 6
	v_readlane_b32 s9, v253, 7
	s_nop 4
.LBB0_1158:
	s_or_b64 exec, exec, s[10:11]
	s_waitcnt vmcnt(0)

.LBB0_1489:
	s_or_b64 exec, exec, s[8:9]
	s_mov_b64 s[8:9], exec
	v_mbcnt_lo_u32_b32 v2, s8, 0
	v_mbcnt_hi_u32_b32 v2, s9, v2
	v_cmp_eq_u32_e32 vcc, 0, v2
	s_waitcnt vmcnt(0)
	buffer_inv sc1
	s_and_saveexec_b64 s[10:11], vcc
	s_cbranch_execz .LBB0_1491
	s_bcnt1_i32_b64 s8, s[8:9]
	v_mov_b32_e32 v2, s8
	v_readlane_b32 s8, v253, 6
	v_readlane_b32 s9, v253, 7
	s_nop 4
.LBB0_1491:
	s_or_b64 exec, exec, s[10:11]
	s_waitcnt vmcnt(0)

.LBB0_1544:
	s_or_b64 exec, exec, s[8:9]
	s_mov_b64 s[8:9], exec
	v_mbcnt_lo_u32_b32 v2, s8, 0
	v_mbcnt_hi_u32_b32 v2, s9, v2
	v_cmp_eq_u32_e32 vcc, 0, v2
	s_waitcnt vmcnt(0)
	buffer_inv sc1
	s_and_saveexec_b64 s[10:11], vcc
	s_cbranch_execz .LBB0_1546
	s_bcnt1_i32_b64 s8, s[8:9]
	v_mov_b32_e32 v2, s8
	v_readlane_b32 s8, v253, 6
	v_readlane_b32 s9, v253, 7
	s_nop 4
.LBB0_1546:
	s_or_b64 exec, exec, s[10:11]
	s_waitcnt vmcnt(0)

.LBB0_1606:
	s_or_b64 exec, exec, s[8:9]
	s_mov_b64 s[8:9], exec
	v_mbcnt_lo_u32_b32 v2, s8, 0
	v_mbcnt_hi_u32_b32 v2, s9, v2
	v_cmp_eq_u32_e32 vcc, 0, v2
	s_waitcnt vmcnt(0)
	buffer_inv sc1
	s_and_saveexec_b64 s[10:11], vcc
	s_cbranch_execz .LBB0_1608
	s_bcnt1_i32_b64 s8, s[8:9]
	v_mov_b32_e32 v2, s8
	v_readlane_b32 s8, v253, 6
	v_readlane_b32 s9, v253, 7
	s_nop 4
.LBB0_1608:
	s_or_b64 exec, exec, s[10:11]
	s_waitcnt vmcnt(0)

.LBB0_1703:
	s_or_b64 exec, exec, s[8:9]
	s_mov_b64 s[8:9], exec
	v_mbcnt_lo_u32_b32 v2, s8, 0
	v_mbcnt_hi_u32_b32 v2, s9, v2
	v_cmp_eq_u32_e32 vcc, 0, v2
	s_waitcnt vmcnt(0)
	buffer_inv sc1
	s_and_saveexec_b64 s[10:11], vcc
	s_cbranch_execz .LBB0_1705
	s_bcnt1_i32_b64 s8, s[8:9]
	v_mov_b32_e32 v2, s8
	v_readlane_b32 s8, v253, 6
	v_readlane_b32 s9, v253, 7
	s_nop 4
.LBB0_1705:
	s_or_b64 exec, exec, s[10:11]
	s_waitcnt vmcnt(0)

.LBB0_2046:
	s_or_b64 exec, exec, s[8:9]
	s_mov_b64 s[8:9], exec
	v_mbcnt_lo_u32_b32 v2, s8, 0
	v_mbcnt_hi_u32_b32 v2, s9, v2
	v_cmp_eq_u32_e32 vcc, 0, v2
	s_waitcnt vmcnt(0)
	buffer_inv sc1
	s_and_saveexec_b64 s[10:11], vcc
	s_cbranch_execz .LBB0_2048
	s_bcnt1_i32_b64 s8, s[8:9]
	v_mov_b32_e32 v2, s8
	v_readlane_b32 s8, v253, 6
	v_readlane_b32 s9, v253, 7
	s_nop 4
.LBB0_2048:
	s_or_b64 exec, exec, s[10:11]
	s_waitcnt vmcnt(0)

.LBB0_2143:
	s_or_b64 exec, exec, s[8:9]
	s_mov_b64 s[8:9], exec
	v_mbcnt_lo_u32_b32 v2, s8, 0
	v_mbcnt_hi_u32_b32 v2, s9, v2
	v_cmp_eq_u32_e32 vcc, 0, v2
	s_waitcnt vmcnt(0)
	buffer_inv sc1
	s_and_saveexec_b64 s[10:11], vcc
	s_cbranch_execz .LBB0_2145
	s_bcnt1_i32_b64 s8, s[8:9]
	v_mov_b32_e32 v2, s8
	v_readlane_b32 s8, v253, 6
	v_readlane_b32 s9, v253, 7
	s_nop 4
.LBB0_2145:
	s_or_b64 exec, exec, s[10:11]
	s_waitcnt vmcnt(0)

.LBB0_2219:
	s_or_b64 exec, exec, s[8:9]
	v_cvt_f32_u32_e32 v7, v5
	s_waitcnt vmcnt(0)
	v_readfirstlane_b32 s8, v6
	v_sub_u32_e32 v6, 0, v5
	v_rcp_iflag_f32_e32 v7, v7
	v_add_u32_e32 v8, s8, v2
	v_mul_f32_e32 v7, 0x4f7ffffe, v7
	v_cvt_u32_f32_e32 v7, v7
	v_mul_lo_u32 v2, v6, v7
	v_mul_hi_u32 v2, v7, v2
	v_add_u32_e32 v2, v7, v2
	v_mul_hi_u32 v2, v8, v2
	v_mul_lo_u32 v6, v2, v5
	v_sub_u32_e32 v6, v8, v6
	v_add_u32_e32 v7, 1, v2
	v_cmp_ge_u32_e32 vcc, v6, v5
	s_nop 1
	v_cndmask_b32_e32 v2, v2, v7, vcc
	v_sub_u32_e32 v7, v6, v5
	v_cndmask_b32_e32 v6, v6, v7, vcc
	v_add_u32_e32 v7, 1, v2
	v_cmp_ge_u32_e32 vcc, v6, v5
	v_add_u32_e32 v6, 1, v8
	s_nop 0
	v_cndmask_b32_e32 v2, v2, v7, vcc
	v_mul_lo_u32 v7, v5, v2
	v_add_u32_e32 v5, v7, v5
	v_cmp_ne_u32_e32 vcc, v6, v5
	s_and_saveexec_b64 s[8:9], vcc
	s_xor_b64 s[8:9], exec, s[8:9]
	s_cbranch_execz .LBB0_2233
	v_readlane_b32 s10, v253, 10
	v_readlane_b32 s11, v253, 11
	s_waitcnt lgkmcnt(0)
	s_nop 3
	global_load_dword v4, v3, s[10:11] sc1
	s_waitcnt vmcnt(0)
	v_cmp_eq_u32_e32 vcc, v4, v2
	s_and_saveexec_b64 s[10:11], vcc
	s_cbranch_execz .LBB0_2232
	s_mov_b32 s21, 1
	s_mov_b64 s[12:13], 0
	s_branch .LBB0_2223

.LBB0_2250:
	s_or_b64 exec, exec, s[8:9]
	s_mov_b64 s[8:9], exec
	v_mbcnt_lo_u32_b32 v2, s8, 0
	v_mbcnt_hi_u32_b32 v2, s9, v2
	v_cmp_eq_u32_e32 vcc, 0, v2
	s_waitcnt vmcnt(0)
	buffer_inv sc1
	s_and_saveexec_b64 s[10:11], vcc
	s_cbranch_execz .LBB0_2252
	s_bcnt1_i32_b64 s8, s[8:9]
	v_mov_b32_e32 v2, s8
	v_readlane_b32 s8, v253, 6
	v_readlane_b32 s9, v253, 7
	s_nop 4
.LBB0_2252:
	s_or_b64 exec, exec, s[10:11]
	s_waitcnt vmcnt(0)

.LBB0_2348:
	s_bcnt1_i32_b64 s8, s[8:9]
	v_mov_b32_e32 v2, s8
	v_readlane_b32 s8, v253, 6
	v_readlane_b32 s9, v253, 7
	s_nop 4
	s_getpc_b64 s[98:99]
